# mid-step barrier in sel fast steps + write-through sc1 stores in up-proj epilogue
# speedup vs baseline: 1.0460x; 1.0231x over previous
.LBB0_1323:
	s_and_b32 s23, s9, 1
	s_andn2_b64 vcc, exec, s[0:1]
	s_mul_i32 s1, s23, 0x4800
	s_mul_i32 s0, s23, 0x1800
	s_cbranch_vccnz .LBB0_1330
	s_add_i32 s10, s22, 1
	s_cmp_ge_u32 s10, s20
	s_cbranch_scc1 .Lsel_generic
	v_cmp_neq_f32_e32 vcc, 0, v243
	s_cmp_lg_u64 vcc, 0
	s_cbranch_scc1 .Lsel_generic
	s_cmp_eq_u64 s[6:7], 0
	s_cbranch_scc1 .Lsel_noa
	s_lshr_b32 s6, s9, 2
	s_and_b32 s6, s6, 0x3ffffff8
	s_waitcnt lgkmcnt(0)
	v_add3_u32 v251, s1, v205, v204
	v_add_u32_e32 v16, s6, v209
	s_add_i32 s1, s1, s0
	ds_read_b128 v[50:53], v251
	ds_read_b128 v[54:57], v251 offset:32
	ds_read_b128 v[58:61], v251 offset:64
	ds_read_b128 v[62:65], v251 offset:96
	ds_read_b128 v[66:69], v251 offset:4608
	ds_read_b128 v[70:73], v251 offset:4640
	ds_read_b128 v[74:77], v251 offset:4672
	ds_read_b128 v[78:81], v251 offset:4704
	ds_read_b64 v[16:17], v16
	v_add3_u32 v250, s1, v242, v244
	s_waitcnt lgkmcnt(8)
	v_mfma_f32_32x32x16_bf16 v[146:161], v[50:53], v[114:117], 0
	ds_read_b64_tr_b16 v[212:213], v250 offset:36864
	ds_read_b64_tr_b16 v[214:215], v250 offset:38400
	s_waitcnt lgkmcnt(9)
	v_mfma_f32_32x32x16_bf16 v[146:161], v[54:57], v[118:121], v[146:161]
	ds_read_b64_tr_b16 v[216:217], v250 offset:36928
	ds_read_b64_tr_b16 v[218:219], v250 offset:38464
	s_waitcnt lgkmcnt(10)
	v_mfma_f32_32x32x16_bf16 v[146:161], v[58:61], v[122:125], v[146:161]
	ds_read_b64_tr_b16 v[220:221], v250 offset:39936
	ds_read_b64_tr_b16 v[222:223], v250 offset:41472
	s_waitcnt lgkmcnt(11)
	v_mfma_f32_32x32x16_bf16 v[146:161], v[62:65], v[126:129], v[146:161]
	ds_read_b64_tr_b16 v[224:225], v250 offset:40000
	ds_read_b64_tr_b16 v[226:227], v250 offset:41536
	s_waitcnt lgkmcnt(8)
	v_and_b32_e32 v16, s28, v16
	v_and_b32_e32 v17, s29, v17
	v_cmp_eq_u64_e32 vcc, 0, v[16:17]
	s_nop 2
	v_mfma_f32_32x32x16_bf16 v[162:177], v[66:69], v[114:117], 0
	ds_read_b64_tr_b16 v[228:229], v250 offset:43008
	ds_read_b64_tr_b16 v[230:231], v250 offset:44544
	v_exp_f32_e32 v8, v146
	v_exp_f32_e32 v9, v147
	v_exp_f32_e32 v10, v148
	v_exp_f32_e32 v11, v149
	v_exp_f32_e32 v12, v150
	v_exp_f32_e32 v13, v151
	v_exp_f32_e32 v14, v152
	v_exp_f32_e32 v15, v153
	v_cvt_pk_bf16_f32 v178, v8, v9
	v_cvt_pk_bf16_f32 v179, v10, v11
	v_cvt_pk_bf16_f32 v180, v12, v13
	v_mfma_f32_32x32x16_bf16 v[162:177], v[70:73], v[118:121], v[162:177]
	ds_read_b64_tr_b16 v[232:233], v250 offset:43072
	ds_read_b64_tr_b16 v[234:235], v250 offset:44608
	v_cvt_pk_bf16_f32 v181, v14, v15
	v_add_f32_e32 v8, v8, v9
	v_add_f32_e32 v10, v10, v11
	v_add_f32_e32 v12, v12, v13
	v_add_f32_e32 v14, v14, v15
	v_add_f32_e32 v8, v8, v10
	v_add_f32_e32 v12, v12, v14
	v_add_f32_e32 v202, v8, v12
	v_cndmask_b32_e64 v178, v178, 0, vcc
	v_cndmask_b32_e64 v179, v179, 0, vcc
	v_cndmask_b32_e64 v180, v180, 0, vcc
	v_cndmask_b32_e64 v181, v181, 0, vcc
	v_mfma_f32_32x32x16_bf16 v[162:177], v[74:77], v[122:125], v[162:177]
	ds_read_b64_tr_b16 v[236:237], v250 offset:46080
	ds_read_b64_tr_b16 v[238:239], v250 offset:47616
	v_exp_f32_e32 v8, v154
	v_exp_f32_e32 v9, v155
	v_exp_f32_e32 v10, v156
	v_exp_f32_e32 v11, v157
	v_exp_f32_e32 v12, v158
	v_exp_f32_e32 v13, v159
	v_exp_f32_e32 v14, v160
	v_exp_f32_e32 v15, v161
	v_cvt_pk_bf16_f32 v182, v8, v9
	v_cvt_pk_bf16_f32 v183, v10, v11
	v_cvt_pk_bf16_f32 v184, v12, v13
	v_cvt_pk_bf16_f32 v185, v14, v15
	v_mfma_f32_32x32x16_bf16 v[162:177], v[78:81], v[126:129], v[162:177]
	ds_read_b64_tr_b16 v[4:5], v250 offset:46144
	s_waitcnt lgkmcnt(11)
	ds_read_b64_tr_b16 v[6:7], v250 offset:47680
	v_add_f32_e32 v8, v8, v9
	v_add_f32_e32 v10, v10, v11
	v_add_f32_e32 v12, v12, v13
	v_add_f32_e32 v14, v14, v15
	v_add_f32_e32 v8, v8, v10
	v_add_f32_e32 v12, v12, v14
	v_add_f32_e32 v8, v8, v12
	v_add_f32_e32 v202, v202, v8
	v_cndmask_b32_e64 v182, v182, 0, vcc
	v_cndmask_b32_e64 v183, v183, 0, vcc
	v_cndmask_b32_e64 v184, v184, 0, vcc
	v_cndmask_b32_e64 v185, v185, 0, vcc
	v_mfma_f32_32x32x16_bf16 v[18:33], v[212:215], v[178:181], v[18:33]
	v_exp_f32_e32 v8, v162
	v_exp_f32_e32 v9, v163
	v_exp_f32_e32 v10, v164
	v_exp_f32_e32 v11, v165
	v_exp_f32_e32 v12, v166
	v_exp_f32_e32 v13, v167
	v_exp_f32_e32 v14, v168
	v_exp_f32_e32 v15, v169
	v_cvt_pk_bf16_f32 v186, v8, v9
	v_cvt_pk_bf16_f32 v187, v10, v11
	v_cvt_pk_bf16_f32 v188, v12, v13
	v_cvt_pk_bf16_f32 v189, v14, v15
	v_mfma_f32_32x32x16_bf16 v[34:49], v[216:219], v[178:181], v[34:49]
	s_xor_b32 s0, s23, 1
	s_mul_i32 s1, s0, 0x4800
	s_mulk_i32 s0, 0x6000
	v_add_u32_e32 v207, s1, v206
	s_waitcnt vmcnt(2)
	ds_write_b128 v207, v[134:137]
	ds_write_b128 v207, v[130:133] offset:16
	v_add_f32_e32 v8, v8, v9
	v_add_f32_e32 v10, v10, v11
	v_add_f32_e32 v12, v12, v13
	v_add_f32_e32 v14, v14, v15
	v_add_f32_e32 v8, v8, v10
	v_add_f32_e32 v12, v12, v14
	v_add_f32_e32 v8, v8, v12
	v_add_f32_e32 v202, v202, v8
	v_cndmask_b32_e64 v186, v186, 0, vcc
	v_cndmask_b32_e64 v187, v187, 0, vcc
	v_cndmask_b32_e64 v188, v188, 0, vcc
	v_cndmask_b32_e64 v189, v189, 0, vcc
	s_waitcnt lgkmcnt(12)
	v_mfma_f32_32x32x16_bf16 v[18:33], v[220:223], v[182:185], v[18:33]
	v_exp_f32_e32 v8, v170
	v_exp_f32_e32 v9, v171
	v_exp_f32_e32 v10, v172
	v_exp_f32_e32 v11, v173
	v_exp_f32_e32 v12, v174
	v_exp_f32_e32 v13, v175
	v_exp_f32_e32 v14, v176
	v_exp_f32_e32 v15, v177
	v_cvt_pk_bf16_f32 v190, v8, v9
	v_cvt_pk_bf16_f32 v191, v10, v11
	v_cvt_pk_bf16_f32 v192, v12, v13
	v_cvt_pk_bf16_f32 v193, v14, v15
	s_waitcnt lgkmcnt(10)
	v_mfma_f32_32x32x16_bf16 v[34:49], v[224:227], v[182:185], v[34:49]
	v_add_u32_e32 v207, s0, v208
	s_waitcnt vmcnt(0)
	ds_write_b128 v207, v[142:145] offset:36864
	ds_write_b128 v207, v[138:141] offset:36880
	v_add_f32_e32 v8, v8, v9
	v_add_f32_e32 v10, v10, v11
	v_add_f32_e32 v12, v12, v13
	v_add_f32_e32 v14, v14, v15
	v_add_f32_e32 v8, v8, v10
	v_add_f32_e32 v12, v12, v14
	v_add_f32_e32 v8, v8, v12
	v_add_f32_e32 v202, v202, v8
	v_cndmask_b32_e64 v190, v190, 0, vcc
	v_cndmask_b32_e64 v191, v191, 0, vcc
	v_cndmask_b32_e64 v192, v192, 0, vcc
	v_cndmask_b32_e64 v193, v193, 0, vcc
	s_waitcnt lgkmcnt(10)
	v_mfma_f32_32x32x16_bf16 v[18:33], v[228:231], v[186:189], v[18:33]
	v_cndmask_b32_e64 v202, v202, 0, vcc
	v_add_f32_e32 v252, v2, v202
	v_mov_b32_e32 v2, v252
	s_waitcnt lgkmcnt(8)
	v_mfma_f32_32x32x16_bf16 v[34:49], v[232:235], v[186:189], v[34:49]
	s_waitcnt lgkmcnt(0)
	s_barrier
	v_mov_b32_e32 v16, v252
	s_nop 1
	v_mfma_f32_32x32x16_bf16 v[18:33], v[236:239], v[190:193], v[18:33]
	v_permlane32_swap_b32_e32 v2, v16
	v_max_f32_e32 v16, v16, v16
	v_mfma_f32_32x32x16_bf16 v[34:49], v[4:7], v[190:193], v[34:49]
	v_max_f32_e32 v2, v2, v2
	v_max_f32_e32 v2, v2, v16
	v_cmp_lt_f32_e32 vcc, s15, v2
	s_cbranch_vccnz .Lsel_shift
	s_branch .Lsel_fast_tail
.Lsel_noa:
	s_cmp_eq_u64 s[34:35], 0
	s_cbranch_scc1 .Lsel_none
	s_lshr_b32 s6, s9, 2
	s_and_b32 s6, s6, 0x3ffffff8
	s_waitcnt lgkmcnt(0)
	v_add3_u32 v251, s1, v205, v204
	v_add_u32_e32 v16, s6, v209
	s_add_i32 s1, s1, s0
	ds_read_b128 v[50:53], v251 offset:9216
	ds_read_b128 v[54:57], v251 offset:9248
	ds_read_b128 v[58:61], v251 offset:9280
	ds_read_b128 v[62:65], v251 offset:9312
	ds_read_b128 v[66:69], v251 offset:13824
	ds_read_b128 v[70:73], v251 offset:13856
	ds_read_b128 v[74:77], v251 offset:13888
	ds_read_b128 v[78:81], v251 offset:13920
	ds_read_b64 v[16:17], v16
	v_add3_u32 v250, s1, v242, v244
	s_waitcnt lgkmcnt(8)
	v_mfma_f32_32x32x16_bf16 v[146:161], v[50:53], v[114:117], 0
	ds_read_b64_tr_b16 v[212:213], v250 offset:49152
	ds_read_b64_tr_b16 v[214:215], v250 offset:50688
	s_waitcnt lgkmcnt(9)
	v_mfma_f32_32x32x16_bf16 v[146:161], v[54:57], v[118:121], v[146:161]
	ds_read_b64_tr_b16 v[216:217], v250 offset:49216
	ds_read_b64_tr_b16 v[218:219], v250 offset:50752
	s_waitcnt lgkmcnt(10)
	v_mfma_f32_32x32x16_bf16 v[146:161], v[58:61], v[122:125], v[146:161]
	ds_read_b64_tr_b16 v[220:221], v250 offset:52224
	ds_read_b64_tr_b16 v[222:223], v250 offset:53760
	s_waitcnt lgkmcnt(11)
	v_mfma_f32_32x32x16_bf16 v[146:161], v[62:65], v[126:129], v[146:161]
	ds_read_b64_tr_b16 v[224:225], v250 offset:52288
	ds_read_b64_tr_b16 v[226:227], v250 offset:53824
	s_waitcnt lgkmcnt(8)
	v_and_b32_e32 v16, s26, v16
	v_and_b32_e32 v17, s27, v17
	v_cmp_eq_u64_e32 vcc, 0, v[16:17]
	s_nop 2
	v_mfma_f32_32x32x16_bf16 v[162:177], v[66:69], v[114:117], 0
	ds_read_b64_tr_b16 v[228:229], v250 offset:55296
	ds_read_b64_tr_b16 v[230:231], v250 offset:56832
	v_exp_f32_e32 v8, v146
	v_exp_f32_e32 v9, v147
	v_exp_f32_e32 v10, v148
	v_exp_f32_e32 v11, v149
	v_exp_f32_e32 v12, v150
	v_exp_f32_e32 v13, v151
	v_exp_f32_e32 v14, v152
	v_exp_f32_e32 v15, v153
	v_cvt_pk_bf16_f32 v178, v8, v9
	v_cvt_pk_bf16_f32 v179, v10, v11
	v_cvt_pk_bf16_f32 v180, v12, v13
	v_mfma_f32_32x32x16_bf16 v[162:177], v[70:73], v[118:121], v[162:177]
	ds_read_b64_tr_b16 v[232:233], v250 offset:55360
	ds_read_b64_tr_b16 v[234:235], v250 offset:56896
	v_cvt_pk_bf16_f32 v181, v14, v15
	v_add_f32_e32 v8, v8, v9
	v_add_f32_e32 v10, v10, v11
	v_add_f32_e32 v12, v12, v13
	v_add_f32_e32 v14, v14, v15
	v_add_f32_e32 v8, v8, v10
	v_add_f32_e32 v12, v12, v14
	v_add_f32_e32 v202, v8, v12
	v_cndmask_b32_e64 v178, v178, 0, vcc
	v_cndmask_b32_e64 v179, v179, 0, vcc
	v_cndmask_b32_e64 v180, v180, 0, vcc
	v_cndmask_b32_e64 v181, v181, 0, vcc
	v_mfma_f32_32x32x16_bf16 v[162:177], v[74:77], v[122:125], v[162:177]
	ds_read_b64_tr_b16 v[236:237], v250 offset:58368
	ds_read_b64_tr_b16 v[238:239], v250 offset:59904
	v_exp_f32_e32 v8, v154
	v_exp_f32_e32 v9, v155
	v_exp_f32_e32 v10, v156
	v_exp_f32_e32 v11, v157
	v_exp_f32_e32 v12, v158
	v_exp_f32_e32 v13, v159
	v_exp_f32_e32 v14, v160
	v_exp_f32_e32 v15, v161
	v_cvt_pk_bf16_f32 v182, v8, v9
	v_cvt_pk_bf16_f32 v183, v10, v11
	v_cvt_pk_bf16_f32 v184, v12, v13
	v_cvt_pk_bf16_f32 v185, v14, v15
	v_mfma_f32_32x32x16_bf16 v[162:177], v[78:81], v[126:129], v[162:177]
	ds_read_b64_tr_b16 v[4:5], v250 offset:58432
	s_waitcnt lgkmcnt(11)
	ds_read_b64_tr_b16 v[6:7], v250 offset:59968
	v_add_f32_e32 v8, v8, v9
	v_add_f32_e32 v10, v10, v11
	v_add_f32_e32 v12, v12, v13
	v_add_f32_e32 v14, v14, v15
	v_add_f32_e32 v8, v8, v10
	v_add_f32_e32 v12, v12, v14
	v_add_f32_e32 v8, v8, v12
	v_add_f32_e32 v202, v202, v8
	v_cndmask_b32_e64 v182, v182, 0, vcc
	v_cndmask_b32_e64 v183, v183, 0, vcc
	v_cndmask_b32_e64 v184, v184, 0, vcc
	v_cndmask_b32_e64 v185, v185, 0, vcc
	v_mfma_f32_32x32x16_bf16 v[18:33], v[212:215], v[178:181], v[18:33]
	v_exp_f32_e32 v8, v162
	v_exp_f32_e32 v9, v163
	v_exp_f32_e32 v10, v164
	v_exp_f32_e32 v11, v165
	v_exp_f32_e32 v12, v166
	v_exp_f32_e32 v13, v167
	v_exp_f32_e32 v14, v168
	v_exp_f32_e32 v15, v169
	v_cvt_pk_bf16_f32 v186, v8, v9
	v_cvt_pk_bf16_f32 v187, v10, v11
	v_cvt_pk_bf16_f32 v188, v12, v13
	v_cvt_pk_bf16_f32 v189, v14, v15
	v_mfma_f32_32x32x16_bf16 v[34:49], v[216:219], v[178:181], v[34:49]
	s_xor_b32 s0, s23, 1
	s_mul_i32 s1, s0, 0x4800
	s_mulk_i32 s0, 0x6000
	v_add_u32_e32 v207, s1, v206
	s_waitcnt vmcnt(2)
	ds_write_b128 v207, v[134:137]
	ds_write_b128 v207, v[130:133] offset:16
	v_add_f32_e32 v8, v8, v9
	v_add_f32_e32 v10, v10, v11
	v_add_f32_e32 v12, v12, v13
	v_add_f32_e32 v14, v14, v15
	v_add_f32_e32 v8, v8, v10
	v_add_f32_e32 v12, v12, v14
	v_add_f32_e32 v8, v8, v12
	v_add_f32_e32 v202, v202, v8
	v_cndmask_b32_e64 v186, v186, 0, vcc
	v_cndmask_b32_e64 v187, v187, 0, vcc
	v_cndmask_b32_e64 v188, v188, 0, vcc
	v_cndmask_b32_e64 v189, v189, 0, vcc
	s_waitcnt lgkmcnt(12)
	v_mfma_f32_32x32x16_bf16 v[18:33], v[220:223], v[182:185], v[18:33]
	v_exp_f32_e32 v8, v170
	v_exp_f32_e32 v9, v171
	v_exp_f32_e32 v10, v172
	v_exp_f32_e32 v11, v173
	v_exp_f32_e32 v12, v174
	v_exp_f32_e32 v13, v175
	v_exp_f32_e32 v14, v176
	v_exp_f32_e32 v15, v177
	v_cvt_pk_bf16_f32 v190, v8, v9
	v_cvt_pk_bf16_f32 v191, v10, v11
	v_cvt_pk_bf16_f32 v192, v12, v13
	v_cvt_pk_bf16_f32 v193, v14, v15
	s_waitcnt lgkmcnt(10)
	v_mfma_f32_32x32x16_bf16 v[34:49], v[224:227], v[182:185], v[34:49]
	v_add_u32_e32 v207, s0, v208
	s_waitcnt vmcnt(0)
	ds_write_b128 v207, v[142:145] offset:36864
	ds_write_b128 v207, v[138:141] offset:36880
	v_add_f32_e32 v8, v8, v9
	v_add_f32_e32 v10, v10, v11
	v_add_f32_e32 v12, v12, v13
	v_add_f32_e32 v14, v14, v15
	v_add_f32_e32 v8, v8, v10
	v_add_f32_e32 v12, v12, v14
	v_add_f32_e32 v8, v8, v12
	v_add_f32_e32 v202, v202, v8
	v_cndmask_b32_e64 v190, v190, 0, vcc
	v_cndmask_b32_e64 v191, v191, 0, vcc
	v_cndmask_b32_e64 v192, v192, 0, vcc
	v_cndmask_b32_e64 v193, v193, 0, vcc
	s_waitcnt lgkmcnt(10)
	v_mfma_f32_32x32x16_bf16 v[18:33], v[228:231], v[186:189], v[18:33]
	v_cndmask_b32_e64 v202, v202, 0, vcc
	v_add_f32_e32 v252, v2, v202
	v_mov_b32_e32 v2, v252
	s_waitcnt lgkmcnt(8)
	v_mfma_f32_32x32x16_bf16 v[34:49], v[232:235], v[186:189], v[34:49]
	s_waitcnt lgkmcnt(0)
	s_barrier
	v_mov_b32_e32 v16, v252
	s_nop 1
	v_mfma_f32_32x32x16_bf16 v[18:33], v[236:239], v[190:193], v[18:33]
	v_permlane32_swap_b32_e32 v2, v16
	v_max_f32_e32 v16, v16, v16
	v_mfma_f32_32x32x16_bf16 v[34:49], v[4:7], v[190:193], v[34:49]
	v_max_f32_e32 v2, v2, v2
	v_max_f32_e32 v2, v2, v16
	v_cmp_lt_f32_e32 vcc, s15, v2
	s_cbranch_vccnz .Lsel_shift
	s_branch .Lsel_fast_tail
.Lsel_none:
	v_mov_b32_e32 v252, v2
	s_xor_b32 s0, s23, 1
	s_mul_i32 s1, s0, 0x4800
	v_add_u32_e32 v207, s1, v206
	s_mulk_i32 s0, 0x6000
	s_waitcnt vmcnt(2)
	ds_write_b128 v207, v[134:137]
	ds_write_b128 v207, v[130:133] offset:16
	v_add_u32_e32 v207, s0, v208
	s_waitcnt vmcnt(0)
	ds_write_b128 v207, v[142:145] offset:36864
	ds_write_b128 v207, v[138:141] offset:36880
	s_waitcnt lgkmcnt(0)
	s_barrier
	s_branch .Lsel_fast_tail

.LBB0_1330:
	s_and_b64 vcc, exec, s[10:11]
	s_cbranch_vccz .LBB0_1358
	s_lshr_b32 s6, s9, 2
	s_and_b32 s6, s6, 0x3ffffff8
	s_waitcnt lgkmcnt(0)
	v_add3_u32 v251, s1, v205, v204
	v_add_u32_e32 v16, s6, v209
	s_add_i32 s1, s1, s0
	ds_read_b128 v[50:53], v251
	ds_read_b128 v[54:57], v251 offset:32
	ds_read_b128 v[58:61], v251 offset:64
	ds_read_b128 v[62:65], v251 offset:96
	ds_read_b128 v[66:69], v251 offset:4608
	ds_read_b128 v[70:73], v251 offset:4640
	ds_read_b128 v[74:77], v251 offset:4672
	ds_read_b128 v[78:81], v251 offset:4704
	ds_read_b64 v[16:17], v16
	v_add3_u32 v250, s1, v242, v244
	s_waitcnt lgkmcnt(8)
	v_mfma_f32_32x32x16_bf16 v[146:161], v[50:53], v[114:117], 0
	ds_read_b128 v[82:85], v251 offset:9216
	ds_read_b128 v[86:89], v251 offset:9248
	s_waitcnt lgkmcnt(9)
	v_mfma_f32_32x32x16_bf16 v[146:161], v[54:57], v[118:121], v[146:161]
	ds_read_b128 v[90:93], v251 offset:9280
	ds_read_b128 v[94:97], v251 offset:9312
	s_waitcnt lgkmcnt(10)
	v_mfma_f32_32x32x16_bf16 v[146:161], v[58:61], v[122:125], v[146:161]
	ds_read_b128 v[98:101], v251 offset:13824
	ds_read_b128 v[102:105], v251 offset:13856
	s_waitcnt lgkmcnt(11)
	v_mfma_f32_32x32x16_bf16 v[146:161], v[62:65], v[126:129], v[146:161]
	ds_read_b128 v[106:109], v251 offset:13888
	ds_read_b128 v[110:113], v251 offset:13920
	s_waitcnt lgkmcnt(8)
	v_and_b32_e32 v240, s28, v16
	v_and_b32_e32 v241, s29, v17
	v_and_b32_e32 v16, s26, v16
	v_and_b32_e32 v17, s27, v17
	v_cmp_eq_u64_e32 vcc, 0, v[240:241]
	v_cmp_eq_u64_e64 s[6:7], 0, v[16:17]
	v_mfma_f32_32x32x16_bf16 v[162:177], v[66:69], v[114:117], 0
	ds_read_b64_tr_b16 v[212:213], v250 offset:36864
	ds_read_b64_tr_b16 v[214:215], v250 offset:38400
	v_exp_f32_e32 v8, v146
	v_exp_f32_e32 v9, v147
	v_exp_f32_e32 v10, v148
	v_exp_f32_e32 v11, v149
	v_exp_f32_e32 v12, v150
	v_exp_f32_e32 v13, v151
	v_exp_f32_e32 v14, v152
	v_mfma_f32_32x32x16_bf16 v[162:177], v[70:73], v[118:121], v[162:177]
	ds_read_b64_tr_b16 v[216:217], v250 offset:36928
	ds_read_b64_tr_b16 v[218:219], v250 offset:38464
	v_exp_f32_e32 v15, v153
	v_cvt_pk_bf16_f32 v178, v8, v9
	v_cvt_pk_bf16_f32 v179, v10, v11
	v_cvt_pk_bf16_f32 v180, v12, v13
	v_cvt_pk_bf16_f32 v181, v14, v15
	v_add_f32_e32 v8, v8, v9
	v_add_f32_e32 v10, v10, v11
	v_add_f32_e32 v12, v12, v13
	v_mfma_f32_32x32x16_bf16 v[162:177], v[74:77], v[122:125], v[162:177]
	ds_read_b64_tr_b16 v[220:221], v250 offset:39936
	ds_read_b64_tr_b16 v[222:223], v250 offset:41472
	v_add_f32_e32 v14, v14, v15
	v_add_f32_e32 v8, v8, v10
	v_add_f32_e32 v12, v12, v14
	v_add_f32_e32 v202, v8, v12
	v_cndmask_b32_e64 v178, v178, 0, vcc
	v_cndmask_b32_e64 v179, v179, 0, vcc
	v_cndmask_b32_e64 v180, v180, 0, vcc
	v_cndmask_b32_e64 v181, v181, 0, vcc
	v_mfma_f32_32x32x16_bf16 v[162:177], v[78:81], v[126:129], v[162:177]
	ds_read_b64_tr_b16 v[224:225], v250 offset:40000
	s_waitcnt lgkmcnt(11)
	ds_read_b64_tr_b16 v[226:227], v250 offset:41536
	v_exp_f32_e32 v8, v154
	v_exp_f32_e32 v9, v155
	v_exp_f32_e32 v10, v156
	v_exp_f32_e32 v11, v157
	v_exp_f32_e32 v12, v158
	v_exp_f32_e32 v13, v159
	v_exp_f32_e32 v14, v160
	v_exp_f32_e32 v15, v161
	v_mfma_f32_32x32x16_bf16 v[50:65], v[82:85], v[114:117], 0
	ds_read_b64_tr_b16 v[228:229], v250 offset:43008
	ds_read_b64_tr_b16 v[230:231], v250 offset:44544
	v_cvt_pk_bf16_f32 v182, v8, v9
	v_cvt_pk_bf16_f32 v183, v10, v11
	v_cvt_pk_bf16_f32 v184, v12, v13
	v_cvt_pk_bf16_f32 v185, v14, v15
	v_add_f32_e32 v8, v8, v9
	v_add_f32_e32 v10, v10, v11
	v_add_f32_e32 v12, v12, v13
	v_add_f32_e32 v14, v14, v15
	v_mfma_f32_32x32x16_bf16 v[50:65], v[86:89], v[118:121], v[50:65]
	ds_read_b64_tr_b16 v[232:233], v250 offset:43072
	s_waitcnt lgkmcnt(11)
	ds_read_b64_tr_b16 v[234:235], v250 offset:44608
	v_add_f32_e32 v8, v8, v10
	v_add_f32_e32 v12, v12, v14
	v_add_f32_e32 v8, v8, v12
	v_add_f32_e32 v202, v202, v8
	v_cndmask_b32_e64 v182, v182, 0, vcc
	v_cndmask_b32_e64 v183, v183, 0, vcc
	v_cndmask_b32_e64 v184, v184, 0, vcc
	v_cndmask_b32_e64 v185, v185, 0, vcc
	v_mfma_f32_32x32x16_bf16 v[50:65], v[90:93], v[122:125], v[50:65]
	ds_read_b64_tr_b16 v[236:237], v250 offset:46080
	ds_read_b64_tr_b16 v[238:239], v250 offset:47616
	v_exp_f32_e32 v8, v162
	v_exp_f32_e32 v9, v163
	v_exp_f32_e32 v10, v164
	v_exp_f32_e32 v11, v165
	v_exp_f32_e32 v12, v166
	v_exp_f32_e32 v13, v167
	v_exp_f32_e32 v14, v168
	v_exp_f32_e32 v15, v169
	v_mfma_f32_32x32x16_bf16 v[50:65], v[94:97], v[126:129], v[50:65]
	ds_read_b64_tr_b16 v[4:5], v250 offset:46144
	s_waitcnt lgkmcnt(11)
	ds_read_b64_tr_b16 v[6:7], v250 offset:47680
	v_cvt_pk_bf16_f32 v186, v8, v9
	v_cvt_pk_bf16_f32 v187, v10, v11
	v_cvt_pk_bf16_f32 v188, v12, v13
	v_cvt_pk_bf16_f32 v189, v14, v15
	v_add_f32_e32 v8, v8, v9
	v_add_f32_e32 v10, v10, v11
	v_add_f32_e32 v12, v12, v13
	v_add_f32_e32 v14, v14, v15
	v_mfma_f32_32x32x16_bf16 v[66:81], v[98:101], v[114:117], 0
	ds_read_b64_tr_b16 v[146:147], v250 offset:49152
	ds_read_b64_tr_b16 v[148:149], v250 offset:50688
	v_add_f32_e32 v8, v8, v10
	v_add_f32_e32 v12, v12, v14
	v_add_f32_e32 v8, v8, v12
	v_add_f32_e32 v202, v202, v8
	v_cndmask_b32_e64 v186, v186, 0, vcc
	v_cndmask_b32_e64 v187, v187, 0, vcc
	v_cndmask_b32_e64 v188, v188, 0, vcc
	v_cndmask_b32_e64 v189, v189, 0, vcc
	v_mfma_f32_32x32x16_bf16 v[66:81], v[102:105], v[118:121], v[66:81]
	ds_read_b64_tr_b16 v[150:151], v250 offset:49216
	s_waitcnt lgkmcnt(11)
	ds_read_b64_tr_b16 v[152:153], v250 offset:50752
	v_exp_f32_e32 v8, v170
	v_exp_f32_e32 v9, v171
	v_exp_f32_e32 v10, v172
	v_exp_f32_e32 v11, v173
	v_exp_f32_e32 v12, v174
	v_exp_f32_e32 v13, v175
	v_exp_f32_e32 v14, v176
	v_exp_f32_e32 v15, v177
	v_mfma_f32_32x32x16_bf16 v[66:81], v[106:109], v[122:125], v[66:81]
	ds_read_b64_tr_b16 v[154:155], v250 offset:52224
	ds_read_b64_tr_b16 v[156:157], v250 offset:53760
	v_cvt_pk_bf16_f32 v190, v8, v9
	v_cvt_pk_bf16_f32 v191, v10, v11
	v_cvt_pk_bf16_f32 v192, v12, v13
	v_cvt_pk_bf16_f32 v193, v14, v15
	v_add_f32_e32 v8, v8, v9
	v_add_f32_e32 v10, v10, v11
	v_add_f32_e32 v12, v12, v13
	v_add_f32_e32 v14, v14, v15
	v_mfma_f32_32x32x16_bf16 v[66:81], v[110:113], v[126:129], v[66:81]
	ds_read_b64_tr_b16 v[158:159], v250 offset:52288
	s_waitcnt lgkmcnt(11)
	ds_read_b64_tr_b16 v[160:161], v250 offset:53824
	v_add_f32_e32 v8, v8, v10
	v_add_f32_e32 v12, v12, v14
	v_add_f32_e32 v8, v8, v12
	v_add_f32_e32 v202, v202, v8
	v_cndmask_b32_e64 v190, v190, 0, vcc
	v_cndmask_b32_e64 v191, v191, 0, vcc
	v_cndmask_b32_e64 v192, v192, 0, vcc
	v_cndmask_b32_e64 v193, v193, 0, vcc
	v_mfma_f32_32x32x16_bf16 v[18:33], v[212:215], v[178:181], v[18:33]
	v_exp_f32_e32 v8, v50
	v_exp_f32_e32 v9, v51
	v_exp_f32_e32 v10, v52
	v_exp_f32_e32 v11, v53
	v_exp_f32_e32 v12, v54
	v_exp_f32_e32 v13, v55
	v_exp_f32_e32 v14, v56
	v_exp_f32_e32 v15, v57
	v_mfma_f32_32x32x16_bf16 v[34:49], v[216:219], v[178:181], v[34:49]
	ds_read_b64_tr_b16 v[162:163], v250 offset:55296
	ds_read_b64_tr_b16 v[164:165], v250 offset:56832
	v_cvt_pk_bf16_f32 v178, v8, v9
	v_cvt_pk_bf16_f32 v179, v10, v11
	v_cvt_pk_bf16_f32 v180, v12, v13
	v_cvt_pk_bf16_f32 v181, v14, v15
	v_add_f32_e32 v8, v8, v9
	v_add_f32_e32 v10, v10, v11
	v_add_f32_e32 v12, v12, v13
	v_add_f32_e32 v14, v14, v15
	v_mfma_f32_32x32x16_bf16 v[18:33], v[220:223], v[182:185], v[18:33]
	ds_read_b64_tr_b16 v[166:167], v250 offset:55360
	s_waitcnt lgkmcnt(11)
	ds_read_b64_tr_b16 v[168:169], v250 offset:56896
	v_add_f32_e32 v8, v8, v10
	v_add_f32_e32 v12, v12, v14
	v_add_f32_e32 v203, v8, v12
	v_cndmask_b32_e64 v178, v178, 0, s[6:7]
	v_cndmask_b32_e64 v179, v179, 0, s[6:7]
	v_cndmask_b32_e64 v180, v180, 0, s[6:7]
	v_cndmask_b32_e64 v181, v181, 0, s[6:7]
	v_exp_f32_e32 v8, v58
	v_mfma_f32_32x32x16_bf16 v[34:49], v[224:227], v[182:185], v[34:49]
	ds_read_b64_tr_b16 v[170:171], v250 offset:58368
	ds_read_b64_tr_b16 v[172:173], v250 offset:59904
	v_exp_f32_e32 v9, v59
	v_exp_f32_e32 v10, v60
	v_exp_f32_e32 v11, v61
	v_exp_f32_e32 v12, v62
	v_exp_f32_e32 v13, v63
	v_exp_f32_e32 v14, v64
	v_exp_f32_e32 v15, v65
	v_cvt_pk_bf16_f32 v182, v8, v9
	v_mfma_f32_32x32x16_bf16 v[18:33], v[228:231], v[186:189], v[18:33]
	ds_read_b64_tr_b16 v[174:175], v250 offset:58432
	s_waitcnt lgkmcnt(11)
	ds_read_b64_tr_b16 v[176:177], v250 offset:59968
	v_cvt_pk_bf16_f32 v183, v10, v11
	v_cvt_pk_bf16_f32 v184, v12, v13
	v_cvt_pk_bf16_f32 v185, v14, v15
	v_add_f32_e32 v8, v8, v9
	v_add_f32_e32 v10, v10, v11
	v_add_f32_e32 v12, v12, v13
	v_add_f32_e32 v14, v14, v15
	v_add_f32_e32 v8, v8, v10
	v_mfma_f32_32x32x16_bf16 v[34:49], v[232:235], v[186:189], v[34:49]
	s_xor_b32 s0, s23, 1
	s_mul_i32 s1, s0, 0x4800
	s_mulk_i32 s0, 0x6000
	v_add_u32_e32 v207, s1, v206
	s_waitcnt vmcnt(2)
	ds_write_b128 v207, v[134:137]
	ds_write_b128 v207, v[130:133] offset:16
	v_add_f32_e32 v12, v12, v14
	v_add_f32_e32 v8, v8, v12
	v_add_f32_e32 v203, v203, v8
	v_cndmask_b32_e64 v182, v182, 0, s[6:7]
	v_cndmask_b32_e64 v183, v183, 0, s[6:7]
	v_cndmask_b32_e64 v184, v184, 0, s[6:7]
	v_cndmask_b32_e64 v185, v185, 0, s[6:7]
	v_exp_f32_e32 v8, v66
	v_mfma_f32_32x32x16_bf16 v[18:33], v[236:239], v[190:193], v[18:33]
	v_exp_f32_e32 v9, v67
	v_exp_f32_e32 v10, v68
	v_exp_f32_e32 v11, v69
	v_exp_f32_e32 v12, v70
	v_exp_f32_e32 v13, v71
	v_exp_f32_e32 v14, v72
	v_exp_f32_e32 v15, v73
	v_cvt_pk_bf16_f32 v186, v8, v9
	v_mfma_f32_32x32x16_bf16 v[34:49], v[4:7], v[190:193], v[34:49]
	v_add_u32_e32 v207, s0, v208
	s_waitcnt vmcnt(0)
	ds_write_b128 v207, v[142:145] offset:36864
	s_waitcnt lgkmcnt(11)
	ds_write_b128 v207, v[138:141] offset:36880
	v_cvt_pk_bf16_f32 v187, v10, v11
	v_cvt_pk_bf16_f32 v188, v12, v13
	v_cvt_pk_bf16_f32 v189, v14, v15
	v_add_f32_e32 v8, v8, v9
	v_add_f32_e32 v10, v10, v11
	v_add_f32_e32 v12, v12, v13
	v_add_f32_e32 v14, v14, v15
	v_add_f32_e32 v8, v8, v10
	v_mfma_f32_32x32x16_bf16 v[18:33], v[146:149], v[178:181], v[18:33]
	v_add_f32_e32 v12, v12, v14
	v_add_f32_e32 v8, v8, v12
	v_add_f32_e32 v203, v203, v8
	v_cndmask_b32_e64 v186, v186, 0, s[6:7]
	v_cndmask_b32_e64 v187, v187, 0, s[6:7]
	v_cndmask_b32_e64 v188, v188, 0, s[6:7]
	v_cndmask_b32_e64 v189, v189, 0, s[6:7]
	v_exp_f32_e32 v8, v74
	v_mfma_f32_32x32x16_bf16 v[34:49], v[150:153], v[178:181], v[34:49]
	v_exp_f32_e32 v9, v75
	v_exp_f32_e32 v10, v76
	v_exp_f32_e32 v11, v77
	v_exp_f32_e32 v12, v78
	v_exp_f32_e32 v13, v79
	v_exp_f32_e32 v14, v80
	v_exp_f32_e32 v15, v81
	v_cvt_pk_bf16_f32 v190, v8, v9
	v_mfma_f32_32x32x16_bf16 v[18:33], v[154:157], v[182:185], v[18:33]
	s_waitcnt lgkmcnt(0)
	s_barrier
	v_cvt_pk_bf16_f32 v191, v10, v11
	v_cvt_pk_bf16_f32 v192, v12, v13
	v_cvt_pk_bf16_f32 v193, v14, v15
	v_add_f32_e32 v8, v8, v9
	v_add_f32_e32 v10, v10, v11
	v_add_f32_e32 v12, v12, v13
	v_add_f32_e32 v14, v14, v15
	v_add_f32_e32 v8, v8, v10
	v_mfma_f32_32x32x16_bf16 v[34:49], v[158:161], v[182:185], v[34:49]
	v_add_f32_e32 v12, v12, v14
	v_add_f32_e32 v8, v8, v12
	v_add_f32_e32 v203, v203, v8
	v_cndmask_b32_e64 v190, v190, 0, s[6:7]
	v_cndmask_b32_e64 v191, v191, 0, s[6:7]
	v_cndmask_b32_e64 v192, v192, 0, s[6:7]
	v_cndmask_b32_e64 v193, v193, 0, s[6:7]
	v_cndmask_b32_e64 v202, v202, 0, vcc
	v_mfma_f32_32x32x16_bf16 v[18:33], v[162:165], v[186:189], v[18:33]
	v_cndmask_b32_e64 v203, v203, 0, s[6:7]
	v_add_f32_e32 v202, v202, v203
	v_add_f32_e32 v252, v2, v202
	v_mfma_f32_32x32x16_bf16 v[34:49], v[166:169], v[186:189], v[34:49]
	v_mov_b32_e32 v2, v252
	v_mov_b32_e32 v4, v252
	s_nop 1
	v_mfma_f32_32x32x16_bf16 v[18:33], v[170:173], v[190:193], v[18:33]
	v_permlane32_swap_b32_e32 v2, v4
	v_max_f32_e32 v4, v4, v4
	v_mfma_f32_32x32x16_bf16 v[34:49], v[174:177], v[190:193], v[34:49]
	v_max_f32_e32 v2, v2, v2
	v_max_f32_e32 v2, v2, v4
	v_cmp_lt_f32_e32 vcc, s15, v2
	s_cbranch_vccz .Lsel_fast_tail
.Lsel_shift:
	s_nop 0
	v_cndmask_b32_e32 v4, 0, v248, vcc
	v_cndmask_b32_e32 v2, 1.0, v249, vcc
	v_add_f32_e32 v243, v243, v4
	v_mul_f32_e32 v252, v252, v2
	v_pk_mul_f32 v[32:33], v[32:33], v[2:3] op_sel_hi:[1,0]
	v_pk_mul_f32 v[30:31], v[30:31], v[2:3] op_sel_hi:[1,0]
	v_pk_mul_f32 v[28:29], v[28:29], v[2:3] op_sel_hi:[1,0]
	v_pk_mul_f32 v[26:27], v[26:27], v[2:3] op_sel_hi:[1,0]
	v_pk_mul_f32 v[24:25], v[24:25], v[2:3] op_sel_hi:[1,0]
	v_pk_mul_f32 v[22:23], v[22:23], v[2:3] op_sel_hi:[1,0]
	v_pk_mul_f32 v[20:21], v[20:21], v[2:3] op_sel_hi:[1,0]
	v_pk_mul_f32 v[18:19], v[18:19], v[2:3] op_sel_hi:[1,0]
	v_pk_mul_f32 v[48:49], v[48:49], v[2:3] op_sel_hi:[1,0]
	v_pk_mul_f32 v[46:47], v[46:47], v[2:3] op_sel_hi:[1,0]
	v_pk_mul_f32 v[44:45], v[44:45], v[2:3] op_sel_hi:[1,0]
	v_pk_mul_f32 v[42:43], v[42:43], v[2:3] op_sel_hi:[1,0]
	v_pk_mul_f32 v[40:41], v[40:41], v[2:3] op_sel_hi:[1,0]
	v_pk_mul_f32 v[38:39], v[38:39], v[2:3] op_sel_hi:[1,0]
	v_pk_mul_f32 v[36:37], v[36:37], v[2:3] op_sel_hi:[1,0]
	v_pk_mul_f32 v[34:35], v[34:35], v[2:3] op_sel_hi:[1,0]
	s_branch .Lsel_fast_tail

.Lsel_fast_tail:
	s_add_i32 s22, s22, 2
	s_add_i32 s9, s9, 1
	s_cmp_eq_u32 s31, s22
	v_add_u32_e32 v246, 0x80, v246
	s_cbranch_scc1 .Lsel_fast_exit
	v_mov_b32_e32 v2, v252
	s_branch .Lsel_loop_nocopy

.LBB0_2725:
	s_lshl_b32 s0, s54, 8
	s_waitcnt lgkmcnt(0)
	v_mul_f32_e32 v128, v128, v178
	v_mul_f32_e32 v124, v124, v178
	v_mul_f32_e32 v129, v129, v178
	v_mul_f32_e32 v125, v125, v178
	s_or_b32 s0, s0, s47
	v_max_f32_e32 v128, 0, v128
	v_max_f32_e32 v124, 0, v124
	v_max_f32_e32 v129, 0, v129
	v_max_f32_e32 v125, 0, v125
	v_mul_f32_e32 v130, v130, v178
	v_mul_f32_e32 v126, v126, v178
	v_mul_f32_e32 v131, v131, v178
	v_mul_f32_e32 v127, v127, v178
	v_lshl_add_u32 v136, v185, 3, s0
	v_pk_mul_f32 v[128:129], v[128:129], v[128:129]
	v_pk_mul_f32 v[124:125], v[124:125], v[124:125]
	v_max_f32_e32 v130, 0, v130
	v_max_f32_e32 v126, 0, v126
	v_max_f32_e32 v131, 0, v131
	v_max_f32_e32 v127, 0, v127
	v_ashrrev_i32_e32 v137, 31, v136
	v_pk_mul_f32 v[130:131], v[130:131], v[130:131]
	v_pk_mul_f32 v[138:139], v[126:127], v[126:127]
	v_cvt_pk_bf16_f32 v126, v128, v129
	v_cvt_pk_bf16_f32 v128, v124, v125
	v_lshlrev_b64 v[124:125], 13, v[174:175]
	v_cvt_pk_bf16_f32 v127, v130, v131
	v_lshl_add_u64 v[130:131], s[22:23], 0, v[124:125]
	v_lshlrev_b64 v[124:125], 1, v[136:137]
	v_mul_f32_e32 v116, v116, v178
	v_mul_f32_e32 v117, v117, v178
	v_cvt_pk_bf16_f32 v129, v138, v139
	v_lshl_add_u64 v[130:131], v[130:131], 0, v[124:125]
	v_max_f32_e32 v116, 0, v116
	v_max_f32_e32 v117, 0, v117
	global_store_dwordx4 v[130:131], v[126:129], off sc1
	v_mul_f32_e32 v120, v120, v178
	v_mul_f32_e32 v121, v121, v178
	v_pk_mul_f32 v[126:127], v[116:117], v[116:117]
	v_mul_f32_e32 v117, v118, v178
	v_mul_f32_e32 v116, v122, v178
	v_max_f32_e32 v118, 0, v117
	v_mul_f32_e32 v117, v123, v178
	v_mul_f32_e32 v119, v119, v178
	v_max_f32_e32 v120, 0, v120
	v_max_f32_e32 v121, 0, v121
	v_max_f32_e32 v116, 0, v116
	v_max_f32_e32 v117, 0, v117
	v_max_f32_e32 v119, 0, v119
	v_pk_mul_f32 v[120:121], v[120:121], v[120:121]
	v_pk_mul_f32 v[122:123], v[116:117], v[116:117]
	v_pk_mul_f32 v[128:129], v[118:119], v[118:119]
	v_mul_f32_e32 v108, v108, v179
	v_mul_f32_e32 v109, v109, v179
	v_cvt_pk_bf16_f32 v116, v120, v121
	v_cvt_pk_bf16_f32 v117, v122, v123
	v_cvt_pk_bf16_f32 v118, v126, v127
	v_cvt_pk_bf16_f32 v119, v128, v129
	v_max_f32_e32 v108, 0, v108
	v_max_f32_e32 v109, 0, v109
	global_store_dwordx4 v[130:131], v[116:119], off offset:256 sc1
	v_mul_f32_e32 v112, v112, v179
	v_mul_f32_e32 v113, v113, v179
	v_pk_mul_f32 v[116:117], v[108:109], v[108:109]
	v_mul_f32_e32 v109, v110, v179
	v_max_f32_e32 v112, 0, v112
	v_max_f32_e32 v113, 0, v113
	v_mul_f32_e32 v108, v114, v179
	v_max_f32_e32 v110, 0, v109
	v_mul_f32_e32 v109, v115, v179
	v_pk_mul_f32 v[112:113], v[112:113], v[112:113]
	v_max_f32_e32 v108, 0, v108
	v_max_f32_e32 v109, 0, v109
	v_mul_f32_e32 v111, v111, v179
	v_max_f32_e32 v111, 0, v111
	v_pk_mul_f32 v[114:115], v[108:109], v[108:109]
	v_cvt_pk_bf16_f32 v108, v112, v113
	v_lshlrev_b64 v[112:113], 13, v[172:173]
	v_pk_mul_f32 v[118:119], v[110:111], v[110:111]
	v_lshl_add_u64 v[112:113], s[22:23], 0, v[112:113]
	v_mul_f32_e32 v100, v100, v179
	v_mul_f32_e32 v101, v101, v179
	v_cvt_pk_bf16_f32 v109, v114, v115
	v_cvt_pk_bf16_f32 v110, v116, v117
	v_cvt_pk_bf16_f32 v111, v118, v119
	v_lshl_add_u64 v[112:113], v[112:113], 0, v[124:125]
	v_max_f32_e32 v100, 0, v100
	v_max_f32_e32 v101, 0, v101
	global_store_dwordx4 v[112:113], v[108:111], off sc1
	v_mul_f32_e32 v104, v104, v179
	v_mul_f32_e32 v105, v105, v179
	v_pk_mul_f32 v[108:109], v[100:101], v[100:101]
	v_mul_f32_e32 v101, v102, v179
	v_mul_f32_e32 v100, v106, v179
	v_max_f32_e32 v102, 0, v101
	v_mul_f32_e32 v101, v107, v179
	v_mul_f32_e32 v103, v103, v179
	v_max_f32_e32 v104, 0, v104
	v_max_f32_e32 v105, 0, v105
	v_max_f32_e32 v100, 0, v100
	v_max_f32_e32 v101, 0, v101
	v_max_f32_e32 v103, 0, v103
	v_pk_mul_f32 v[104:105], v[104:105], v[104:105]
	v_pk_mul_f32 v[106:107], v[100:101], v[100:101]
	v_pk_mul_f32 v[110:111], v[102:103], v[102:103]
	v_mul_f32_e32 v92, v92, v148
	v_mul_f32_e32 v93, v93, v148
	v_cvt_pk_bf16_f32 v100, v104, v105
	v_cvt_pk_bf16_f32 v101, v106, v107
	v_cvt_pk_bf16_f32 v102, v108, v109
	v_cvt_pk_bf16_f32 v103, v110, v111
	v_max_f32_e32 v92, 0, v92
	v_max_f32_e32 v93, 0, v93
	global_store_dwordx4 v[112:113], v[100:103], off offset:256 sc1
	v_mul_f32_e32 v96, v96, v148
	v_mul_f32_e32 v97, v97, v148
	v_pk_mul_f32 v[100:101], v[92:93], v[92:93]
	v_mul_f32_e32 v93, v94, v148
	v_max_f32_e32 v96, 0, v96
	v_max_f32_e32 v97, 0, v97
	v_mul_f32_e32 v92, v98, v148
	v_max_f32_e32 v94, 0, v93
	v_mul_f32_e32 v93, v99, v148
	v_pk_mul_f32 v[96:97], v[96:97], v[96:97]
	v_max_f32_e32 v92, 0, v92
	v_max_f32_e32 v93, 0, v93
	v_mul_f32_e32 v95, v95, v148
	v_max_f32_e32 v95, 0, v95
	v_pk_mul_f32 v[98:99], v[92:93], v[92:93]
	v_cvt_pk_bf16_f32 v92, v96, v97
	v_lshlrev_b64 v[96:97], 13, v[170:171]
	v_pk_mul_f32 v[102:103], v[94:95], v[94:95]
	v_lshl_add_u64 v[96:97], s[22:23], 0, v[96:97]
	v_mul_f32_e32 v84, v84, v148
	v_mul_f32_e32 v85, v85, v148
	v_cvt_pk_bf16_f32 v93, v98, v99
	v_cvt_pk_bf16_f32 v94, v100, v101
	v_cvt_pk_bf16_f32 v95, v102, v103
	v_lshl_add_u64 v[96:97], v[96:97], 0, v[124:125]
	v_max_f32_e32 v84, 0, v84
	v_max_f32_e32 v85, 0, v85
	global_store_dwordx4 v[96:97], v[92:95], off sc1
	v_mul_f32_e32 v88, v88, v148
	v_mul_f32_e32 v89, v89, v148
	v_pk_mul_f32 v[92:93], v[84:85], v[84:85]
	v_mul_f32_e32 v85, v86, v148
	v_mul_f32_e32 v84, v90, v148
	v_max_f32_e32 v86, 0, v85
	v_mul_f32_e32 v85, v91, v148
	v_mul_f32_e32 v87, v87, v148
	v_max_f32_e32 v88, 0, v88
	v_max_f32_e32 v89, 0, v89
	v_max_f32_e32 v84, 0, v84
	v_max_f32_e32 v85, 0, v85
	v_max_f32_e32 v87, 0, v87
	v_pk_mul_f32 v[88:89], v[88:89], v[88:89]
	v_pk_mul_f32 v[90:91], v[84:85], v[84:85]
	v_pk_mul_f32 v[94:95], v[86:87], v[86:87]
	v_mul_f32_e32 v76, v76, v149
	v_mul_f32_e32 v77, v77, v149
	v_cvt_pk_bf16_f32 v84, v88, v89
	v_cvt_pk_bf16_f32 v85, v90, v91
	v_cvt_pk_bf16_f32 v86, v92, v93
	v_cvt_pk_bf16_f32 v87, v94, v95
	v_max_f32_e32 v76, 0, v76
	v_max_f32_e32 v77, 0, v77
	global_store_dwordx4 v[96:97], v[84:87], off offset:256 sc1
	v_mul_f32_e32 v80, v80, v149
	v_mul_f32_e32 v81, v81, v149
	v_pk_mul_f32 v[84:85], v[76:77], v[76:77]
	v_mul_f32_e32 v77, v78, v149
	v_max_f32_e32 v80, 0, v80
	v_max_f32_e32 v81, 0, v81
	v_mul_f32_e32 v76, v82, v149
	v_max_f32_e32 v78, 0, v77
	v_mul_f32_e32 v77, v83, v149
	v_pk_mul_f32 v[80:81], v[80:81], v[80:81]
	v_max_f32_e32 v76, 0, v76
	v_max_f32_e32 v77, 0, v77
	v_mul_f32_e32 v79, v79, v149
	v_max_f32_e32 v79, 0, v79
	v_pk_mul_f32 v[82:83], v[76:77], v[76:77]
	v_cvt_pk_bf16_f32 v76, v80, v81
	v_lshlrev_b64 v[80:81], 13, v[168:169]
	v_pk_mul_f32 v[86:87], v[78:79], v[78:79]
	v_lshl_add_u64 v[80:81], s[22:23], 0, v[80:81]
	v_mul_f32_e32 v68, v68, v149
	v_mul_f32_e32 v69, v69, v149
	v_cvt_pk_bf16_f32 v77, v82, v83
	v_cvt_pk_bf16_f32 v78, v84, v85
	v_cvt_pk_bf16_f32 v79, v86, v87
	v_lshl_add_u64 v[80:81], v[80:81], 0, v[124:125]
	v_max_f32_e32 v68, 0, v68
	v_max_f32_e32 v69, 0, v69
	global_store_dwordx4 v[80:81], v[76:79], off sc1
	v_mul_f32_e32 v72, v72, v149
	v_mul_f32_e32 v73, v73, v149
	v_pk_mul_f32 v[76:77], v[68:69], v[68:69]
	v_mul_f32_e32 v69, v70, v149
	v_mul_f32_e32 v68, v74, v149
	v_max_f32_e32 v70, 0, v69
	v_mul_f32_e32 v69, v75, v149
	v_mul_f32_e32 v71, v71, v149
	v_max_f32_e32 v72, 0, v72
	v_max_f32_e32 v73, 0, v73
	v_max_f32_e32 v68, 0, v68
	v_max_f32_e32 v69, 0, v69
	v_max_f32_e32 v71, 0, v71
	v_pk_mul_f32 v[72:73], v[72:73], v[72:73]
	v_pk_mul_f32 v[74:75], v[68:69], v[68:69]
	v_pk_mul_f32 v[78:79], v[70:71], v[70:71]
	v_mul_f32_e32 v60, v60, v140
	v_mul_f32_e32 v61, v61, v140
	v_cvt_pk_bf16_f32 v68, v72, v73
	v_cvt_pk_bf16_f32 v69, v74, v75
	v_cvt_pk_bf16_f32 v70, v76, v77
	v_cvt_pk_bf16_f32 v71, v78, v79
	v_max_f32_e32 v60, 0, v60
	v_max_f32_e32 v61, 0, v61
	global_store_dwordx4 v[80:81], v[68:71], off offset:256 sc1
	v_mul_f32_e32 v64, v64, v140
	v_mul_f32_e32 v65, v65, v140
	v_pk_mul_f32 v[68:69], v[60:61], v[60:61]
	v_mul_f32_e32 v61, v62, v140
	v_max_f32_e32 v64, 0, v64
	v_max_f32_e32 v65, 0, v65
	v_mul_f32_e32 v60, v66, v140
	v_max_f32_e32 v62, 0, v61
	v_mul_f32_e32 v61, v67, v140
	v_pk_mul_f32 v[64:65], v[64:65], v[64:65]
	v_max_f32_e32 v60, 0, v60
	v_max_f32_e32 v61, 0, v61
	v_mul_f32_e32 v63, v63, v140
	v_max_f32_e32 v63, 0, v63
	v_pk_mul_f32 v[66:67], v[60:61], v[60:61]
	v_cvt_pk_bf16_f32 v60, v64, v65
	v_lshlrev_b64 v[64:65], 13, v[134:135]
	v_pk_mul_f32 v[70:71], v[62:63], v[62:63]
	v_lshl_add_u64 v[64:65], s[22:23], 0, v[64:65]
	v_mul_f32_e32 v52, v52, v140
	v_mul_f32_e32 v53, v53, v140
	v_cvt_pk_bf16_f32 v61, v66, v67
	v_cvt_pk_bf16_f32 v62, v68, v69
	v_cvt_pk_bf16_f32 v63, v70, v71
	v_lshl_add_u64 v[64:65], v[64:65], 0, v[124:125]
	v_max_f32_e32 v52, 0, v52
	v_max_f32_e32 v53, 0, v53
	global_store_dwordx4 v[64:65], v[60:63], off sc1
	v_mul_f32_e32 v56, v56, v140
	v_mul_f32_e32 v57, v57, v140
	v_pk_mul_f32 v[60:61], v[52:53], v[52:53]
	v_mul_f32_e32 v53, v54, v140
	v_mul_f32_e32 v52, v58, v140
	v_max_f32_e32 v54, 0, v53
	v_mul_f32_e32 v53, v59, v140
	v_mul_f32_e32 v55, v55, v140
	v_max_f32_e32 v56, 0, v56
	v_max_f32_e32 v57, 0, v57
	v_max_f32_e32 v52, 0, v52
	v_max_f32_e32 v53, 0, v53
	v_max_f32_e32 v55, 0, v55
	v_pk_mul_f32 v[56:57], v[56:57], v[56:57]
	v_pk_mul_f32 v[58:59], v[52:53], v[52:53]
	v_pk_mul_f32 v[62:63], v[54:55], v[54:55]
	v_mul_f32_e32 v44, v44, v141
	v_mul_f32_e32 v45, v45, v141
	v_cvt_pk_bf16_f32 v52, v56, v57
	v_cvt_pk_bf16_f32 v53, v58, v59
	v_cvt_pk_bf16_f32 v54, v60, v61
	v_cvt_pk_bf16_f32 v55, v62, v63
	v_max_f32_e32 v44, 0, v44
	v_max_f32_e32 v45, 0, v45
	global_store_dwordx4 v[64:65], v[52:55], off offset:256 sc1
	v_mul_f32_e32 v48, v48, v141
	v_mul_f32_e32 v49, v49, v141
	v_pk_mul_f32 v[52:53], v[44:45], v[44:45]
	v_mul_f32_e32 v45, v46, v141
	v_max_f32_e32 v48, 0, v48
	v_max_f32_e32 v49, 0, v49
	v_mul_f32_e32 v44, v50, v141
	v_max_f32_e32 v46, 0, v45
	v_mul_f32_e32 v45, v51, v141
	v_pk_mul_f32 v[48:49], v[48:49], v[48:49]
	v_max_f32_e32 v44, 0, v44
	v_max_f32_e32 v45, 0, v45
	v_ashrrev_i32_e32 v167, 31, v166
	v_pk_mul_f32 v[50:51], v[44:45], v[44:45]
	v_cvt_pk_bf16_f32 v44, v48, v49
	v_lshlrev_b64 v[48:49], 13, v[166:167]
	v_lshl_add_u64 v[48:49], s[22:23], 0, v[48:49]
	v_mul_f32_e32 v47, v47, v141
	v_lshl_add_u64 v[48:49], v[48:49], 0, v[124:125]
	s_mov_b64 s[0:1], 0x20000
	v_max_f32_e32 v47, 0, v47
	v_cvt_pk_bf16_f32 v45, v50, v51
	v_lshl_add_u64 v[50:51], v[48:49], 0, s[0:1]
	s_mov_b32 s0, 0x20000
	v_pk_mul_f32 v[54:55], v[46:47], v[46:47]
	v_cvt_pk_bf16_f32 v46, v52, v53
	v_add_co_u32_e32 v52, vcc, s0, v48
	v_mul_f32_e32 v36, v36, v141
	v_mul_f32_e32 v37, v37, v141
	v_cvt_pk_bf16_f32 v47, v54, v55
	v_addc_co_u32_e32 v53, vcc, 0, v49, vcc
	v_max_f32_e32 v36, 0, v36
	v_max_f32_e32 v37, 0, v37
	global_store_dwordx4 v[52:53], v[44:47], off sc1
	v_mul_f32_e32 v40, v40, v141
	v_mul_f32_e32 v41, v41, v141
	v_pk_mul_f32 v[44:45], v[36:37], v[36:37]
	v_mul_f32_e32 v37, v38, v141
	v_mul_f32_e32 v36, v42, v141
	v_max_f32_e32 v38, 0, v37
	v_mul_f32_e32 v37, v43, v141
	v_mul_f32_e32 v39, v39, v141
	v_max_f32_e32 v40, 0, v40
	v_max_f32_e32 v41, 0, v41
	v_max_f32_e32 v36, 0, v36
	v_max_f32_e32 v37, 0, v37
	v_max_f32_e32 v39, 0, v39
	v_pk_mul_f32 v[40:41], v[40:41], v[40:41]
	v_pk_mul_f32 v[42:43], v[36:37], v[36:37]
	v_pk_mul_f32 v[46:47], v[38:39], v[38:39]
	v_mul_f32_e32 v28, v28, v132
	v_mul_f32_e32 v29, v29, v132
	v_cvt_pk_bf16_f32 v36, v40, v41
	v_cvt_pk_bf16_f32 v37, v42, v43
	v_cvt_pk_bf16_f32 v38, v44, v45
	v_cvt_pk_bf16_f32 v39, v46, v47
	v_max_f32_e32 v28, 0, v28
	v_max_f32_e32 v29, 0, v29
	global_store_dwordx4 v[50:51], v[36:39], off offset:256 sc1
	v_mul_f32_e32 v32, v32, v132
	v_mul_f32_e32 v33, v33, v132
	v_pk_mul_f32 v[36:37], v[28:29], v[28:29]
	v_mul_f32_e32 v29, v30, v132
	v_max_f32_e32 v32, 0, v32
	v_max_f32_e32 v33, 0, v33
	v_mul_f32_e32 v28, v34, v132
	v_max_f32_e32 v30, 0, v29
	v_mul_f32_e32 v29, v35, v132
	v_pk_mul_f32 v[32:33], v[32:33], v[32:33]
	v_max_f32_e32 v28, 0, v28
	v_max_f32_e32 v29, 0, v29
	v_mul_f32_e32 v31, v31, v132
	s_mov_b64 s[0:1], 0x40000
	v_max_f32_e32 v31, 0, v31
	v_pk_mul_f32 v[34:35], v[28:29], v[28:29]
	v_cvt_pk_bf16_f32 v28, v32, v33
	v_lshl_add_u64 v[32:33], v[48:49], 0, s[0:1]
	s_mov_b32 s0, 0x40000
	v_pk_mul_f32 v[38:39], v[30:31], v[30:31]
	v_cvt_pk_bf16_f32 v29, v34, v35
	v_add_co_u32_e32 v34, vcc, s0, v48
	v_mul_f32_e32 v20, v20, v132
	v_mul_f32_e32 v21, v21, v132
	v_cvt_pk_bf16_f32 v30, v36, v37
	v_cvt_pk_bf16_f32 v31, v38, v39
	v_addc_co_u32_e32 v35, vcc, 0, v49, vcc
	v_max_f32_e32 v20, 0, v20
	v_max_f32_e32 v21, 0, v21
	global_store_dwordx4 v[34:35], v[28:31], off sc1
	v_mul_f32_e32 v24, v24, v132
	v_mul_f32_e32 v25, v25, v132
	v_pk_mul_f32 v[28:29], v[20:21], v[20:21]
	v_mul_f32_e32 v21, v22, v132
	v_mul_f32_e32 v20, v26, v132
	v_max_f32_e32 v22, 0, v21
	v_mul_f32_e32 v21, v27, v132
	v_mul_f32_e32 v23, v23, v132
	v_max_f32_e32 v24, 0, v24
	v_max_f32_e32 v25, 0, v25
	v_max_f32_e32 v20, 0, v20
	v_max_f32_e32 v21, 0, v21
	v_max_f32_e32 v23, 0, v23
	v_pk_mul_f32 v[24:25], v[24:25], v[24:25]
	v_pk_mul_f32 v[26:27], v[20:21], v[20:21]
	v_pk_mul_f32 v[30:31], v[22:23], v[22:23]
	v_mul_f32_e32 v12, v12, v133
	v_mul_f32_e32 v13, v13, v133
	v_cvt_pk_bf16_f32 v20, v24, v25
	v_cvt_pk_bf16_f32 v21, v26, v27
	v_cvt_pk_bf16_f32 v22, v28, v29
	v_cvt_pk_bf16_f32 v23, v30, v31
	v_max_f32_e32 v12, 0, v12
	v_max_f32_e32 v13, 0, v13
	global_store_dwordx4 v[32:33], v[20:23], off offset:256 sc1
	v_mul_f32_e32 v16, v16, v133
	v_mul_f32_e32 v17, v17, v133
	v_pk_mul_f32 v[20:21], v[12:13], v[12:13]
	v_mul_f32_e32 v13, v14, v133
	v_max_f32_e32 v16, 0, v16
	v_max_f32_e32 v17, 0, v17
	v_mul_f32_e32 v12, v18, v133
	v_max_f32_e32 v14, 0, v13
	v_mul_f32_e32 v13, v19, v133
	v_pk_mul_f32 v[16:17], v[16:17], v[16:17]
	v_max_f32_e32 v12, 0, v12
	v_max_f32_e32 v13, 0, v13
	v_mul_f32_e32 v15, v15, v133
	s_mov_b64 s[0:1], 0x60000
	v_max_f32_e32 v15, 0, v15
	v_pk_mul_f32 v[18:19], v[12:13], v[12:13]
	v_cvt_pk_bf16_f32 v12, v16, v17
	v_lshl_add_u64 v[16:17], v[48:49], 0, s[0:1]
	s_mov_b32 s0, 0x60000
	v_pk_mul_f32 v[22:23], v[14:15], v[14:15]
	v_cvt_pk_bf16_f32 v13, v18, v19
	v_add_co_u32_e32 v18, vcc, s0, v48
	v_mul_f32_e32 v4, v4, v133
	v_mul_f32_e32 v5, v5, v133
	v_cvt_pk_bf16_f32 v14, v20, v21
	v_cvt_pk_bf16_f32 v15, v22, v23
	v_addc_co_u32_e32 v19, vcc, 0, v49, vcc
	v_max_f32_e32 v4, 0, v4
	v_max_f32_e32 v5, 0, v5
	global_store_dwordx4 v[18:19], v[12:15], off sc1
	v_mul_f32_e32 v8, v8, v133
	v_mul_f32_e32 v9, v9, v133
	v_pk_mul_f32 v[12:13], v[4:5], v[4:5]
	v_mul_f32_e32 v5, v6, v133
	v_mul_f32_e32 v4, v10, v133
	v_max_f32_e32 v6, 0, v5
	v_mul_f32_e32 v5, v11, v133
	v_mul_f32_e32 v7, v7, v133
	v_max_f32_e32 v8, 0, v8
	v_max_f32_e32 v9, 0, v9
	v_max_f32_e32 v4, 0, v4
	v_max_f32_e32 v5, 0, v5
	v_max_f32_e32 v7, 0, v7
	v_pk_mul_f32 v[8:9], v[8:9], v[8:9]
	v_pk_mul_f32 v[10:11], v[4:5], v[4:5]
	v_pk_mul_f32 v[14:15], v[6:7], v[6:7]
	v_cvt_pk_bf16_f32 v4, v8, v9
	v_cvt_pk_bf16_f32 v5, v10, v11
	v_cvt_pk_bf16_f32 v6, v12, v13
	v_cvt_pk_bf16_f32 v7, v14, v15
	s_andn2_b64 vcc, exec, s[2:3]
	s_mov_b64 s[0:1], -1
	global_store_dwordx4 v[16:17], v[4:7], off offset:256 sc1
	s_cbranch_vccnz .LBB0_2708
	s_andn2_b64 vcc, exec, s[20:21]
	s_cbranch_vccnz .LBB0_2707
	s_barrier
	s_branch .LBB0_2707
